# pool (rolling prefetch, generic-grid fallback kept) + x-conversion loads batched
# speedup vs baseline: 1.0056x; 1.0056x over previous
.LBB0_382:
	s_or_b64 exec, exec, s[8:9]
	v_mov_b32_e32 v10, v1
	s_waitcnt lgkmcnt(0)
	s_barrier
	s_cmp_lg_u32 s74, 0x10000
	s_cbranch_scc1 .Lpool_generic
	s_xor_b64 s[36:37], s[52:53], -1
	v_add_u32_e32 v3, s75, v1
	v_add_u32_e32 v3, s76, v3
	v_lshrrev_b32_e32 v3, 8, v3
	v_and_b32_e32 v2, 0xff, v1
	v_lshlrev_b32_e32 v2, 4, v2
	v_lshl_or_b32 v2, v3, 17, v2
	s_nop 0
	v_readfirstlane_b32 s100, v3
	v_readfirstlane_b32 s101, v1
	v_and_b32_e32 v3, 0xff, v1
	v_lshlrev_b32_e32 v3, 5, v3
	s_lshl_b32 s30, s64, 13
	s_add_u32 s98, s44, s30
	s_addc_u32 s99, s45, 0
	global_load_dwordx4 v[108:111], v3, s[98:99]
	global_load_dwordx4 v[112:115], v3, s[98:99] offset:16
	s_bfe_u32 s101, s101, 0x20006
	s_add_u32 s39, s101, 1
	s_lshl_b32 s38, s39, 23
	s_sub_u32 s38, 0x3f800000, s38
	s_lshl_b32 s101, 2, s101
	s_sub_u32 s101, s101, 1
	s_add_u32 s8, s84, 0xc000000
	s_addc_u32 s9, s85, 0
	s_mov_b64 s[10:11], s[50:51]
	s_add_u32 s12, s84, 0x14000000
	s_addc_u32 s13, s85, 0
	s_lshl_b32 s39, s101, 12
	s_sub_u32 s40, s8, s39
	s_subb_u32 s41, s9, 0
	s_and_b32 s100, s100, 0x7f
	s_cmp_eq_u32 s100, 0
	s_cselect_b32 s30, s101, 0
	s_mov_b32 s100, 0
	v_mov_b32_e32 v100, 0
	v_mov_b32_e32 v101, 0
	v_mov_b32_e32 v102, 0
	v_mov_b32_e32 v103, 0
	v_mov_b32_e32 v104, 0
	v_mov_b32_e32 v105, 0
	v_mov_b32_e32 v106, 0
	v_mov_b32_e32 v107, 0
	s_cmp_lg_u32 s30, 0
	s_cbranch_scc1 .Lpool_lb_done
	s_sub_u32 s98, s8, 0x1000
	s_subb_u32 s99, s9, 0
	global_load_dwordx4 v[36:39], v2, s[98:99]
	s_cmp_lt_u32 s101, 2
	s_cbranch_scc1 .Lpool_lb_issued
	s_sub_u32 s98, s8, 0x2000
	s_subb_u32 s99, s9, 0
	global_load_dwordx4 v[40:43], v2, s[98:99]
	s_sub_u32 s98, s8, 0x3000
	s_subb_u32 s99, s9, 0
	global_load_dwordx4 v[44:47], v2, s[98:99]
	s_cmp_lt_u32 s101, 4
	s_cbranch_scc1 .Lpool_lb_issued
	s_sub_u32 s98, s8, 0x4000
	s_subb_u32 s99, s9, 0
	global_load_dwordx4 v[48:51], v2, s[98:99]
	s_sub_u32 s98, s8, 0x5000
	s_subb_u32 s99, s9, 0
	global_load_dwordx4 v[52:55], v2, s[98:99]
	s_sub_u32 s98, s8, 0x6000
	s_subb_u32 s99, s9, 0
	global_load_dwordx4 v[56:59], v2, s[98:99]
	s_sub_u32 s98, s8, 0x7000
	s_subb_u32 s99, s9, 0
	global_load_dwordx4 v[60:63], v2, s[98:99]
	s_cmp_lt_u32 s101, 8
	s_cbranch_scc1 .Lpool_lb_issued
	s_sub_u32 s98, s8, 0x8000
	s_subb_u32 s99, s9, 0
	global_load_dwordx4 v[64:67], v2, s[98:99]
	s_sub_u32 s98, s8, 0x9000
	s_subb_u32 s99, s9, 0
	global_load_dwordx4 v[68:71], v2, s[98:99]
	s_sub_u32 s98, s8, 0xa000
	s_subb_u32 s99, s9, 0
	global_load_dwordx4 v[72:75], v2, s[98:99]
	s_sub_u32 s98, s8, 0xb000
	s_subb_u32 s99, s9, 0
	global_load_dwordx4 v[76:79], v2, s[98:99]
	s_sub_u32 s98, s8, 0xc000
	s_subb_u32 s99, s9, 0
	global_load_dwordx4 v[80:83], v2, s[98:99]
	s_sub_u32 s98, s8, 0xd000
	s_subb_u32 s99, s9, 0
	global_load_dwordx4 v[84:87], v2, s[98:99]
	s_sub_u32 s98, s8, 0xe000
	s_subb_u32 s99, s9, 0
	global_load_dwordx4 v[88:91], v2, s[98:99]
	s_sub_u32 s98, s8, 0xf000
	s_subb_u32 s99, s9, 0
	global_load_dwordx4 v[92:95], v2, s[98:99]

.Lpool_fb_7:
	v_lshlrev_b32_e32 v116, 16, v32
	v_and_b32_e32 v117, 0xffff0000, v32
	v_lshlrev_b32_e32 v118, 16, v33
	v_and_b32_e32 v119, 0xffff0000, v33
	v_lshlrev_b32_e32 v120, 16, v34
	v_and_b32_e32 v121, 0xffff0000, v34
	v_lshlrev_b32_e32 v122, 16, v35
	v_and_b32_e32 v123, 0xffff0000, v35
	v_pk_add_f32 v[100:101], v[100:101], v[116:117]
	v_pk_add_f32 v[102:103], v[102:103], v[118:119]
	v_pk_add_f32 v[104:105], v[104:105], v[120:121]
	v_pk_add_f32 v[106:107], v[106:107], v[122:123]
	v_fma_f32 v116, v154, v100, -v116
	v_fma_f32 v117, v154, v101, -v117
	v_fma_f32 v118, v154, v102, -v118
	v_fma_f32 v119, v154, v103, -v119
	v_fma_f32 v120, v154, v104, -v120
	v_fma_f32 v121, v154, v105, -v121
	v_fma_f32 v122, v154, v106, -v122
	v_fma_f32 v123, v154, v107, -v123
	v_mul_f32_e32 v116, v108, v116
	v_mul_f32_e32 v117, v109, v117
	v_mul_f32_e32 v118, v110, v118
	v_mul_f32_e32 v119, v111, v119
	v_mul_f32_e32 v120, v112, v120
	v_mul_f32_e32 v121, v113, v121
	v_mul_f32_e32 v122, v114, v122
	v_mul_f32_e32 v123, v115, v123
	v_lshlrev_b32_e32 v128, 16, v64
	v_and_b32_e32 v129, 0xffff0000, v64
	v_mul_f32_e32 v116, v116, v128
	v_mul_f32_e32 v117, v117, v129
	v_cvt_pk_bf16_f32 v124, v116, v117
	v_lshlrev_b32_e32 v128, 16, v65
	v_and_b32_e32 v129, 0xffff0000, v65
	v_mul_f32_e32 v118, v118, v128
	v_mul_f32_e32 v119, v119, v129
	v_cvt_pk_bf16_f32 v125, v118, v119
	v_lshlrev_b32_e32 v128, 16, v66
	v_and_b32_e32 v129, 0xffff0000, v66
	v_mul_f32_e32 v120, v120, v128
	v_mul_f32_e32 v121, v121, v129
	v_cvt_pk_bf16_f32 v126, v120, v121
	v_lshlrev_b32_e32 v128, 16, v67
	v_and_b32_e32 v129, 0xffff0000, v67
	v_mul_f32_e32 v122, v122, v128
	v_mul_f32_e32 v123, v123, v129
	v_cvt_pk_bf16_f32 v127, v122, v123
	s_add_u32 s98, s12, 0x7000
	s_addc_u32 s99, s13, 0
	global_store_dwordx4 v2, v[124:127], s[98:99]
	v_lshlrev_b32_e32 v116, 16, v96
	v_and_b32_e32 v117, 0xffff0000, v96
	v_lshlrev_b32_e32 v118, 16, v97
	v_and_b32_e32 v119, 0xffff0000, v97
	v_lshlrev_b32_e32 v120, 16, v98
	v_and_b32_e32 v121, 0xffff0000, v98
	v_lshlrev_b32_e32 v122, 16, v99
	v_and_b32_e32 v123, 0xffff0000, v99
	v_pk_add_f32 v[100:101], v[100:101], v[116:117] neg_lo:[0,1] neg_hi:[0,1]
	v_pk_add_f32 v[102:103], v[102:103], v[118:119] neg_lo:[0,1] neg_hi:[0,1]
	v_pk_add_f32 v[104:105], v[104:105], v[120:121] neg_lo:[0,1] neg_hi:[0,1]
	v_pk_add_f32 v[106:107], v[106:107], v[122:123] neg_lo:[0,1] neg_hi:[0,1]
	s_add_u32 s100, s100, 1
	s_mov_b64 s[38:39], exec
	s_branch .LBB0_409
.Lpool_generic:
	s_mov_b32 s8, 0x10000
	v_add_u32_e32 v48, s75, v10
	s_xor_b64 s[36:37], s[52:53], -1
	v_cmp_gt_i32_e32 vcc, s8, v48
	s_and_saveexec_b64 s[38:39], vcc
	s_cbranch_execz .LBB0_409
	s_lshl_b32 s30, s64, 11
	s_lshl_b64 s[8:9], s[30:31], 2
	s_add_u32 s8, s44, s8
	s_addc_u32 s9, s45, s9
	v_lshlrev_b32_sdwa v6, v194, v10 dst_sel:DWORD dst_unused:UNUSED_PAD src0_sel:DWORD src1_sel:BYTE_0
	global_load_dwordx4 v[2:5], v6, s[8:9]
	s_nop 0
	global_load_dwordx4 v[6:9], v6, s[8:9] offset:16
	v_bfe_u32 v11, v10, 6, 2
	v_lshlrev_b32_e64 v49, v11, 2
	v_lshlrev_b32_sdwa v154, v195, v10 dst_sel:DWORD dst_unused:UNUSED_PAD src0_sel:DWORD src1_sel:BYTE_0
	v_sub_u32_e32 v10, 0, v49
	v_ashrrev_i32_e32 v11, 31, v10
	v_readlane_b32 s8, v241, 28
	v_lshlrev_b64 v[10:11], 12, v[10:11]
	v_readlane_b32 s9, v241, 29
	v_or_b32_e32 v10, v10, v154
	v_lshl_add_u64 v[14:15], s[50:51], 0, v[154:155]
	v_add_u32_e32 v50, -2, v49
	v_add_u32_e32 v51, -1, v49
	v_lshl_add_u64 v[16:17], s[8:9], 0, v[154:155]
	v_lshl_add_u64 v[18:19], s[84:85], 0, v[154:155]
	v_lshl_add_u64 v[20:21], s[84:85], 0, v[10:11]
	s_mov_b64 s[40:41], 0
	s_branch .LBB0_385
